# diff-attention: redundant +0 row-sum seed add removed in the first QK gap of each step (ds_read fills the trans wait state); on top of hm3 C=0 first-touch
# baseline (speedup 1.0000x reference)
.LBB0_563:
	s_add_i32 s13, s12, -1
	s_min_u32 s34, s13, s4
	s_lshl_b64 s[30:31], s[34:35], 13
	v_lshl_add_u64 v[2:3], v[224:225], 0, s[30:31]
	global_load_dwordx4 v[196:199], v[2:3], off
	v_add_co_u32_e32 v2, vcc, s1, v218
	s_nop 1
	v_addc_co_u32_e32 v3, vcc, -1, v219, vcc
	global_load_dwordx4 v[200:203], v[2:3], off offset:-4096
	global_load_dwordx4 v[204:207], v[2:3], off
	ds_read_b128 v[2:5], v243 offset:4608
	ds_read_b128 v[6:9], v243
	ds_read_b128 v[12:15], v242 offset:59392
	s_waitcnt lgkmcnt(0)
	v_mfma_f32_32x32x16_bf16 v[160:175], v[6:9], v[12:15], v[96:111]
	ds_read_b128 v[112:115], v243 offset:32
	v_exp_f32_e32 v0, v128
	v_exp_f32_e32 v6, v129
	ds_read_b128 v[116:119], v242 offset:60416
	v_add_f32_e32 v11, v6, v0
	v_cvt_pk_bf16_f32 v10, v0, v6
	v_mfma_f32_32x32x16_bf16 v[144:159], v[2:5], v[12:15], v[96:111]
	ds_read_b128 v[6:9], v243 offset:4640
	v_exp_f32_e32 v0, v130
	v_exp_f32_e32 v120, v131
	v_add_f32_e32 v121, v0, v11
	v_cvt_pk_bf16_f32 v11, v0, v120
	v_add_f32_e32 v0, v120, v121
	s_waitcnt lgkmcnt(1)
	v_mfma_f32_32x32x16_bf16 v[160:175], v[112:115], v[116:119], v[160:175]
	ds_read_b128 v[2:5], v243 offset:64
	ds_read_b128 v[120:123], v242 offset:61440
	v_exp_f32_e32 v12, v132
	v_exp_f32_e32 v13, v133
	v_add_f32_e32 v0, v12, v0
	v_add_f32_e32 v0, v13, v0
	v_cvt_pk_bf16_f32 v12, v12, v13
	s_waitcnt lgkmcnt(2)
	v_mfma_f32_32x32x16_bf16 v[144:159], v[6:9], v[116:119], v[144:159]
	ds_read_b128 v[112:115], v243 offset:4672
	v_exp_f32_e32 v6, v134
	v_exp_f32_e32 v7, v135
	v_add_f32_e32 v0, v6, v0
	v_add_f32_e32 v0, v7, v0
	v_cvt_pk_bf16_f32 v13, v6, v7
	s_waitcnt lgkmcnt(1)
	v_mfma_f32_32x32x16_bf16 v[160:175], v[2:5], v[120:123], v[160:175]
	ds_read_b128 v[116:119], v243 offset:96
	ds_read_b128 v[124:127], v242 offset:62464
	v_exp_f32_e32 v2, v136
	v_exp_f32_e32 v3, v137
	v_add_f32_e32 v0, v2, v0
	v_add_f32_e32 v0, v3, v0
	v_cvt_pk_bf16_f32 v6, v2, v3
	s_waitcnt lgkmcnt(2)
	v_mfma_f32_32x32x16_bf16 v[144:159], v[112:115], v[120:123], v[144:159]
	ds_read_b128 v[2:5], v243 offset:4704
	v_exp_f32_e32 v7, v138
	v_exp_f32_e32 v8, v139
	v_add_f32_e32 v0, v7, v0
	v_add_f32_e32 v0, v8, v0
	v_cvt_pk_bf16_f32 v7, v7, v8
	s_waitcnt lgkmcnt(1)
	v_mfma_f32_32x32x16_bf16 v[160:175], v[116:119], v[124:127], v[160:175]
	ds_read_b64_tr_b16 v[112:113], v244 offset:18432
	ds_read_b64_tr_b16 v[114:115], v244 offset:20992
	v_exp_f32_e32 v8, v140
	v_exp_f32_e32 v9, v141
	v_add_f32_e32 v0, v8, v0
	v_add_f32_e32 v0, v9, v0
	v_cvt_pk_bf16_f32 v8, v8, v9
	s_waitcnt lgkmcnt(2)
	v_mfma_f32_32x32x16_bf16 v[144:159], v[2:5], v[124:127], v[144:159]
	ds_read_b64_tr_b16 v[116:117], v244 offset:18496
	ds_read_b64_tr_b16 v[118:119], v244 offset:21056
	v_exp_f32_e32 v9, v142
	v_exp_f32_e32 v14, v143
	v_add_f32_e32 v0, v9, v0
	v_add_f32_e32 v0, v14, v0
	v_cvt_pk_bf16_f32 v9, v9, v14
	s_waitcnt lgkmcnt(2)
	v_mfma_f32_32x32x16_bf16 v[64:79], v[112:115], v[188:191], v[64:79]
	ds_read_b64_tr_b16 v[120:121], v244 offset:18560
	ds_read_b64_tr_b16 v[122:123], v244 offset:21120
	v_exp_f32_e32 v2, v80
	v_max3_f32 v3, v160, s33, v144
	v_add_f32_e32 v0, v2, v0
	s_waitcnt lgkmcnt(2)
	v_mfma_f32_32x32x16_bf16 v[48:63], v[116:119], v[188:191], v[48:63]
	ds_read_b64_tr_b16 v[112:113], v244 offset:18624
	ds_read_b64_tr_b16 v[114:115], v244 offset:21184
	v_exp_f32_e32 v4, v81
	v_max3_f32 v3, v3, v161, v145
	v_add_f32_e32 v0, v4, v0
	v_cvt_pk_bf16_f32 v2, v2, v4
	s_waitcnt lgkmcnt(2)
	v_mfma_f32_32x32x16_bf16 v[32:47], v[120:123], v[188:191], v[32:47]
	ds_read_b64_tr_b16 v[116:117], v244 offset:23552
	ds_read_b64_tr_b16 v[118:119], v244 offset:26112
	v_exp_f32_e32 v4, v82
	v_max3_f32 v5, v3, v162, v146
	v_add_f32_e32 v0, v4, v0
	s_waitcnt lgkmcnt(2)
	v_mfma_f32_32x32x16_bf16 v[16:31], v[112:115], v[188:191], v[16:31]
	ds_read_b64_tr_b16 v[120:121], v244 offset:23616
	v_exp_f32_e32 v3, v83
	ds_read_b64_tr_b16 v[122:123], v244 offset:26176
	v_add_f32_e32 v0, v3, v0
	v_cvt_pk_bf16_f32 v3, v4, v3
	v_max3_f32 v4, v5, v163, v147
	s_waitcnt lgkmcnt(2)
	v_mfma_f32_32x32x16_bf16 v[64:79], v[116:119], v[184:187], v[64:79]
	ds_read_b64_tr_b16 v[80:81], v244 offset:23680
	ds_read_b64_tr_b16 v[82:83], v244 offset:26240
	v_exp_f32_e32 v5, v84
	v_max3_f32 v14, v4, v164, v148
	v_add_f32_e32 v0, v5, v0
	s_waitcnt lgkmcnt(2)
	v_mfma_f32_32x32x16_bf16 v[48:63], v[120:123], v[184:187], v[48:63]
	ds_read_b64_tr_b16 v[112:113], v244 offset:23744
	v_exp_f32_e32 v4, v85
	ds_read_b64_tr_b16 v[114:115], v244 offset:26304
	v_add_f32_e32 v0, v4, v0
	v_cvt_pk_bf16_f32 v4, v5, v4
	v_max3_f32 v5, v14, v165, v149
	s_waitcnt lgkmcnt(2)
	v_mfma_f32_32x32x16_bf16 v[32:47], v[80:83], v[184:187], v[32:47]
	ds_read_b64_tr_b16 v[116:117], v244 offset:28672
	ds_read_b64_tr_b16 v[118:119], v244 offset:31232
	v_exp_f32_e32 v14, v86
	v_max3_f32 v15, v5, v166, v150
	v_add_f32_e32 v0, v14, v0
	s_waitcnt lgkmcnt(2)
	v_mfma_f32_32x32x16_bf16 v[16:31], v[112:115], v[184:187], v[16:31]
	ds_read_b64_tr_b16 v[80:81], v244 offset:28736
	v_exp_f32_e32 v5, v87
	ds_read_b64_tr_b16 v[82:83], v244 offset:31296
	v_add_f32_e32 v0, v5, v0
	v_cvt_pk_bf16_f32 v5, v14, v5
	v_max3_f32 v14, v15, v167, v151
	s_waitcnt lgkmcnt(2)
	v_mfma_f32_32x32x16_bf16 v[64:79], v[116:119], v[176:179], v[64:79]
	ds_read_b64_tr_b16 v[84:85], v244 offset:28800
	ds_read_b64_tr_b16 v[86:87], v244 offset:31360
	v_exp_f32_e32 v15, v88
	v_max3_f32 v14, v14, v168, v152
	v_add_f32_e32 v0, v15, v0
	s_waitcnt lgkmcnt(2)
	v_mfma_f32_32x32x16_bf16 v[48:63], v[80:83], v[176:179], v[48:63]
	ds_read_b64_tr_b16 v[112:113], v244 offset:28864
	ds_read_b64_tr_b16 v[114:115], v244 offset:31424
	v_exp_f32_e32 v80, v89
	v_max3_f32 v14, v14, v169, v153
	v_add_f32_e32 v0, v80, v0
	v_cvt_pk_bf16_f32 v192, v15, v80
	s_waitcnt lgkmcnt(2)
	v_mfma_f32_32x32x16_bf16 v[32:47], v[84:87], v[176:179], v[32:47]
	ds_read_b64_tr_b16 v[80:81], v244 offset:33792
	ds_read_b64_tr_b16 v[82:83], v244 offset:36352
	v_exp_f32_e32 v15, v90
	v_max3_f32 v14, v14, v170, v154
	v_add_f32_e32 v0, v15, v0
	s_waitcnt lgkmcnt(2)
	v_mfma_f32_32x32x16_bf16 v[16:31], v[112:115], v[176:179], v[16:31]
	ds_read_b64_tr_b16 v[84:85], v244 offset:33856
	ds_read_b64_tr_b16 v[86:87], v244 offset:36416
	v_exp_f32_e32 v88, v91
	v_max3_f32 v14, v14, v171, v155
	v_add_f32_e32 v0, v88, v0
	v_cvt_pk_bf16_f32 v193, v15, v88
	s_waitcnt lgkmcnt(2)
	v_mfma_f32_32x32x16_bf16 v[64:79], v[80:83], v[180:183], v[64:79]
	ds_read_b64_tr_b16 v[88:89], v244 offset:33920
	ds_read_b64_tr_b16 v[90:91], v244 offset:36480
	v_exp_f32_e32 v15, v92
	v_max3_f32 v14, v14, v172, v156
	v_add_f32_e32 v0, v15, v0
	s_waitcnt lgkmcnt(2)
	v_mfma_f32_32x32x16_bf16 v[48:63], v[84:87], v[180:183], v[48:63]
	ds_read_b64_tr_b16 v[80:81], v244 offset:33984
	ds_read_b64_tr_b16 v[82:83], v244 offset:36544
	v_exp_f32_e32 v84, v93
	v_max3_f32 v14, v14, v173, v157
	v_add_f32_e32 v0, v84, v0
	v_cvt_pk_bf16_f32 v194, v15, v84
	s_waitcnt lgkmcnt(2)
	v_mfma_f32_32x32x16_bf16 v[32:47], v[88:91], v[180:183], v[32:47]
	v_exp_f32_e32 v15, v94
	v_max3_f32 v14, v14, v174, v158
	v_add_f32_e32 v0, v15, v0
	s_waitcnt lgkmcnt(0)
	v_mfma_f32_32x32x16_bf16 v[16:31], v[80:83], v[180:183], v[16:31]
	v_exp_f32_e32 v80, v95
	s_nop 0
	v_add_f32_e32 v0, v80, v0
	v_cvt_pk_bf16_f32 v195, v15, v80
	v_max3_f32 v15, v14, v175, v159
	v_mov_b32_e32 v14, v0
	v_cmp_gt_f32_e32 vcc, 1.0, v226
	s_nop 0
	v_permlane32_swap_b32_e32 v0, v14
	s_cbranch_vccz .LBB0_565
	v_pk_mul_f32 v[78:79], v[226:227], v[78:79] op_sel_hi:[0,1]
	v_pk_mul_f32 v[76:77], v[226:227], v[76:77] op_sel_hi:[0,1]
	v_pk_mul_f32 v[74:75], v[226:227], v[74:75] op_sel_hi:[0,1]
	v_pk_mul_f32 v[72:73], v[226:227], v[72:73] op_sel_hi:[0,1]
	v_pk_mul_f32 v[70:71], v[226:227], v[70:71] op_sel_hi:[0,1]
	v_pk_mul_f32 v[68:69], v[226:227], v[68:69] op_sel_hi:[0,1]
	v_pk_mul_f32 v[66:67], v[226:227], v[66:67] op_sel_hi:[0,1]
	v_pk_mul_f32 v[64:65], v[226:227], v[64:65] op_sel_hi:[0,1]
	v_pk_mul_f32 v[62:63], v[226:227], v[62:63] op_sel_hi:[0,1]
	v_pk_mul_f32 v[60:61], v[226:227], v[60:61] op_sel_hi:[0,1]
	v_pk_mul_f32 v[58:59], v[226:227], v[58:59] op_sel_hi:[0,1]
	v_pk_mul_f32 v[56:57], v[226:227], v[56:57] op_sel_hi:[0,1]
	v_pk_mul_f32 v[54:55], v[226:227], v[54:55] op_sel_hi:[0,1]
	v_pk_mul_f32 v[52:53], v[226:227], v[52:53] op_sel_hi:[0,1]
	v_pk_mul_f32 v[50:51], v[226:227], v[50:51] op_sel_hi:[0,1]
	v_pk_mul_f32 v[48:49], v[226:227], v[48:49] op_sel_hi:[0,1]
	v_pk_mul_f32 v[46:47], v[226:227], v[46:47] op_sel_hi:[0,1]
	v_pk_mul_f32 v[44:45], v[226:227], v[44:45] op_sel_hi:[0,1]
	v_pk_mul_f32 v[42:43], v[226:227], v[42:43] op_sel_hi:[0,1]
	v_pk_mul_f32 v[40:41], v[226:227], v[40:41] op_sel_hi:[0,1]
	v_pk_mul_f32 v[38:39], v[226:227], v[38:39] op_sel_hi:[0,1]
	v_pk_mul_f32 v[36:37], v[226:227], v[36:37] op_sel_hi:[0,1]
	v_pk_mul_f32 v[34:35], v[226:227], v[34:35] op_sel_hi:[0,1]
	v_pk_mul_f32 v[32:33], v[226:227], v[32:33] op_sel_hi:[0,1]
	v_pk_mul_f32 v[30:31], v[226:227], v[30:31] op_sel_hi:[0,1]
	v_pk_mul_f32 v[28:29], v[226:227], v[28:29] op_sel_hi:[0,1]
	v_pk_mul_f32 v[26:27], v[226:227], v[26:27] op_sel_hi:[0,1]
	v_pk_mul_f32 v[24:25], v[226:227], v[24:25] op_sel_hi:[0,1]
	v_pk_mul_f32 v[22:23], v[226:227], v[22:23] op_sel_hi:[0,1]
	v_pk_mul_f32 v[20:21], v[226:227], v[20:21] op_sel_hi:[0,1]
	v_pk_mul_f32 v[18:19], v[226:227], v[18:19] op_sel_hi:[0,1]
	v_pk_mul_f32 v[16:17], v[226:227], v[16:17] op_sel_hi:[0,1]

.LBB0_568:
	s_min_u32 s34, s12, s4
	s_waitcnt vmcnt(2)
	ds_write_b128 v241, v[196:199] offset:9216
	s_waitcnt vmcnt(1)
	ds_write_b128 v240, v[200:203] offset:38912
	s_waitcnt vmcnt(0)
	ds_write_b128 v240, v[204:207] offset:49152
	s_lshl_b64 s[30:31], s[34:35], 13
	s_waitcnt lgkmcnt(0)
	s_barrier
	v_lshl_add_u64 v[80:81], v[224:225], 0, s[30:31]
	global_load_dwordx4 v[196:199], v[80:81], off
	global_load_dwordx4 v[200:203], v[218:219], off offset:-4096
	global_load_dwordx4 v[204:207], v[218:219], off
	ds_read_b128 v[176:179], v243 offset:13824
	ds_read_b128 v[80:83], v243 offset:9216
	ds_read_b128 v[180:183], v242 offset:59392
	s_waitcnt lgkmcnt(0)
	v_mfma_f32_32x32x16_bf16 v[128:143], v[80:83], v[180:183], v[112:127]
	ds_read_b128 v[184:187], v243 offset:9248
	v_exp_f32_e32 v15, v160
	v_exp_f32_e32 v80, v161
	ds_read_b128 v[248:251], v242 offset:60416
	v_add_f32_e32 v81, v80, v15
	v_cvt_pk_bf16_f32 v188, v15, v80
	v_exp_f32_e32 v15, v162
	v_exp_f32_e32 v80, v163
	ds_read_b128 v[160:163], v243 offset:13856
	v_add_f32_e32 v81, v15, v81
	v_cvt_pk_bf16_f32 v189, v15, v80
	v_add_f32_e32 v15, v80, v81
	v_mfma_f32_32x32x16_bf16 v[80:95], v[176:179], v[180:183], v[112:127]
	s_waitcnt lgkmcnt(1)
	v_mfma_f32_32x32x16_bf16 v[128:143], v[184:187], v[248:251], v[128:143]
	ds_read_b128 v[176:179], v243 offset:9280
	ds_read_b128 v[180:183], v242 offset:61440
	v_exp_f32_e32 v164, v164
	v_exp_f32_e32 v165, v165
	v_add_f32_e32 v15, v164, v15
	v_cvt_pk_bf16_f32 v190, v164, v165
	v_add_f32_e32 v15, v165, v15
	s_waitcnt lgkmcnt(2)
	v_mfma_f32_32x32x16_bf16 v[80:95], v[160:163], v[248:251], v[80:95]
	ds_read_b128 v[234:237], v243 offset:13888
	v_exp_f32_e32 v160, v166
	v_exp_f32_e32 v161, v167
	v_add_f32_e32 v15, v160, v15
	v_cvt_pk_bf16_f32 v191, v160, v161
	v_add_f32_e32 v15, v161, v15
	s_waitcnt lgkmcnt(1)
	v_mfma_f32_32x32x16_bf16 v[128:143], v[176:179], v[180:183], v[128:143]
	ds_read_b128 v[160:163], v243 offset:9312
	ds_read_b128 v[164:167], v242 offset:62464
	v_exp_f32_e32 v168, v168
	v_exp_f32_e32 v169, v169
	v_add_f32_e32 v15, v168, v15
	v_cvt_pk_bf16_f32 v184, v168, v169
	v_add_f32_e32 v15, v169, v15
	s_waitcnt lgkmcnt(2)
	v_mfma_f32_32x32x16_bf16 v[80:95], v[234:237], v[180:183], v[80:95]
	ds_read_b128 v[176:179], v243 offset:13920
	v_exp_f32_e32 v168, v170
	v_exp_f32_e32 v169, v171
	v_add_f32_e32 v15, v168, v15
	v_cvt_pk_bf16_f32 v185, v168, v169
	v_add_f32_e32 v15, v169, v15
	s_waitcnt lgkmcnt(1)
	v_mfma_f32_32x32x16_bf16 v[128:143], v[160:163], v[164:167], v[128:143]
	ds_read_b64_tr_b16 v[168:169], v244 offset:38912
	ds_read_b64_tr_b16 v[170:171], v244 offset:41472
	v_exp_f32_e32 v160, v172
	v_exp_f32_e32 v161, v173
	v_add_f32_e32 v15, v160, v15
	v_cvt_pk_bf16_f32 v186, v160, v161
	v_add_f32_e32 v15, v161, v15
	s_waitcnt lgkmcnt(2)
	v_mfma_f32_32x32x16_bf16 v[80:95], v[176:179], v[164:167], v[80:95]
	ds_read_b64_tr_b16 v[160:161], v244 offset:38976
	ds_read_b64_tr_b16 v[162:163], v244 offset:41536
	v_exp_f32_e32 v172, v174
	v_exp_f32_e32 v173, v175
	v_add_f32_e32 v15, v172, v15
	v_cvt_pk_bf16_f32 v187, v172, v173
	v_add_f32_e32 v15, v173, v15
	s_waitcnt lgkmcnt(2)
	v_mfma_f32_32x32x16_bf16 v[64:79], v[168:171], v[10:13], v[64:79]
	ds_read_b64_tr_b16 v[164:165], v244 offset:39040
	ds_read_b64_tr_b16 v[166:167], v244 offset:41600
	v_exp_f32_e32 v144, v144
	v_max3_f32 v172, v128, s33, v80
	v_add_f32_e32 v15, v144, v15
	s_waitcnt lgkmcnt(2)
	v_mfma_f32_32x32x16_bf16 v[48:63], v[160:163], v[10:13], v[48:63]
	ds_read_b64_tr_b16 v[168:169], v244 offset:39104
	v_exp_f32_e32 v145, v145
	ds_read_b64_tr_b16 v[170:171], v244 offset:41664
	v_cvt_pk_bf16_f32 v176, v144, v145
	v_max3_f32 v144, v172, v129, v81
	v_add_f32_e32 v15, v145, v15
	s_waitcnt lgkmcnt(2)
	v_mfma_f32_32x32x16_bf16 v[32:47], v[164:167], v[10:13], v[32:47]
	ds_read_b64_tr_b16 v[160:161], v244 offset:44032
	ds_read_b64_tr_b16 v[162:163], v244 offset:46592
	v_exp_f32_e32 v145, v146
	v_max3_f32 v144, v144, v130, v82
	v_add_f32_e32 v15, v145, v15
	s_waitcnt lgkmcnt(2)
	v_mfma_f32_32x32x16_bf16 v[16:31], v[168:171], v[10:13], v[16:31]
	ds_read_b64_tr_b16 v[164:165], v244 offset:44096
	ds_read_b64_tr_b16 v[166:167], v244 offset:46656
	v_exp_f32_e32 v10, v147
	v_max3_f32 v144, v144, v131, v83
	v_cvt_pk_bf16_f32 v177, v145, v10
	v_add_f32_e32 v15, v10, v15
	s_waitcnt lgkmcnt(2)
	v_mfma_f32_32x32x16_bf16 v[64:79], v[160:163], v[6:9], v[64:79]
	ds_read_b64_tr_b16 v[10:11], v244 offset:44160
	ds_read_b64_tr_b16 v[12:13], v244 offset:46720
	v_exp_f32_e32 v148, v148
	v_max3_f32 v160, v144, v132, v84
	v_add_f32_e32 v15, v148, v15
	s_waitcnt lgkmcnt(2)
	v_mfma_f32_32x32x16_bf16 v[48:63], v[164:167], v[6:9], v[48:63]
	ds_read_b64_tr_b16 v[144:145], v244 offset:44224
	v_exp_f32_e32 v149, v149
	ds_read_b64_tr_b16 v[146:147], v244 offset:46784
	v_cvt_pk_bf16_f32 v178, v148, v149
	v_max3_f32 v148, v160, v133, v85
	v_add_f32_e32 v15, v149, v15
	s_waitcnt lgkmcnt(2)
	v_mfma_f32_32x32x16_bf16 v[32:47], v[10:13], v[6:9], v[32:47]
	ds_read_b64_tr_b16 v[160:161], v244 offset:49152
	ds_read_b64_tr_b16 v[162:163], v244 offset:51712
	v_exp_f32_e32 v149, v150
	v_max3_f32 v148, v148, v134, v86
	v_add_f32_e32 v15, v149, v15
	s_waitcnt lgkmcnt(2)
	v_mfma_f32_32x32x16_bf16 v[16:31], v[144:147], v[6:9], v[16:31]
	ds_read_b64_tr_b16 v[10:11], v244 offset:49216
	ds_read_b64_tr_b16 v[12:13], v244 offset:51776
	v_exp_f32_e32 v6, v151
	v_max3_f32 v144, v148, v135, v87
	v_cvt_pk_bf16_f32 v179, v149, v6
	v_add_f32_e32 v15, v6, v15
	s_waitcnt lgkmcnt(2)
	v_mfma_f32_32x32x16_bf16 v[64:79], v[160:163], v[2:5], v[64:79]
	ds_read_b64_tr_b16 v[6:7], v244 offset:49280
	ds_read_b64_tr_b16 v[8:9], v244 offset:51840
	v_exp_f32_e32 v148, v152
	v_max3_f32 v149, v144, v136, v88
	v_add_f32_e32 v15, v148, v15
	s_waitcnt lgkmcnt(2)
	v_mfma_f32_32x32x16_bf16 v[48:63], v[10:13], v[2:5], v[48:63]
	ds_read_b64_tr_b16 v[144:145], v244 offset:49344
	v_exp_f32_e32 v10, v153
	ds_read_b64_tr_b16 v[146:147], v244 offset:51904
	v_cvt_pk_bf16_f32 v180, v148, v10
	v_max3_f32 v148, v149, v137, v89
	v_add_f32_e32 v15, v10, v15
	s_waitcnt lgkmcnt(2)
	v_mfma_f32_32x32x16_bf16 v[32:47], v[6:9], v[2:5], v[32:47]
	ds_read_b64_tr_b16 v[10:11], v244 offset:54272
	ds_read_b64_tr_b16 v[12:13], v244 offset:56832
	v_exp_f32_e32 v149, v154
	v_max3_f32 v148, v148, v138, v90
	v_add_f32_e32 v15, v149, v15
	s_waitcnt lgkmcnt(2)
	v_mfma_f32_32x32x16_bf16 v[16:31], v[144:147], v[2:5], v[16:31]
	ds_read_b64_tr_b16 v[6:7], v244 offset:54336
	ds_read_b64_tr_b16 v[8:9], v244 offset:56896
	v_exp_f32_e32 v2, v155
	v_max3_f32 v144, v148, v139, v91
	v_cvt_pk_bf16_f32 v181, v149, v2
	v_add_f32_e32 v15, v2, v15
	s_waitcnt lgkmcnt(2)
	v_mfma_f32_32x32x16_bf16 v[64:79], v[10:13], v[192:195], v[64:79]
	ds_read_b64_tr_b16 v[2:3], v244 offset:54400
	ds_read_b64_tr_b16 v[4:5], v244 offset:56960
	v_exp_f32_e32 v145, v156
	v_max3_f32 v144, v144, v140, v92
	v_add_f32_e32 v15, v145, v15
	s_waitcnt lgkmcnt(2)
	v_mfma_f32_32x32x16_bf16 v[48:63], v[6:9], v[192:195], v[48:63]
	ds_read_b64_tr_b16 v[10:11], v244 offset:54464
	v_exp_f32_e32 v6, v157
	ds_read_b64_tr_b16 v[12:13], v244 offset:57024
	v_add_f32_e32 v7, v6, v15
	v_cvt_pk_bf16_f32 v182, v145, v6
	v_max3_f32 v6, v144, v141, v93
	s_waitcnt lgkmcnt(2)
	v_mfma_f32_32x32x16_bf16 v[32:47], v[2:5], v[192:195], v[32:47]
	v_exp_f32_e32 v3, v158
	v_max3_f32 v4, v6, v142, v94
	v_add_f32_e32 v2, v3, v7
	s_waitcnt lgkmcnt(0)
	v_mfma_f32_32x32x16_bf16 v[16:31], v[10:13], v[192:195], v[16:31]
	v_exp_f32_e32 v5, v159
	s_nop 0
	v_add_f32_e32 v2, v5, v2
	v_cvt_pk_bf16_f32 v183, v3, v5
	v_max3_f32 v3, v4, v143, v95
	v_mov_b32_e32 v4, v2
	v_cmp_gt_f32_e32 vcc, 1.0, v0
	s_nop 0
	v_permlane32_swap_b32_e32 v2, v4
	s_cbranch_vccz .LBB0_570
	v_pk_mul_f32 v[78:79], v[0:1], v[78:79] op_sel_hi:[0,1]
	v_pk_mul_f32 v[76:77], v[0:1], v[76:77] op_sel_hi:[0,1]
	v_pk_mul_f32 v[74:75], v[0:1], v[74:75] op_sel_hi:[0,1]
	v_pk_mul_f32 v[72:73], v[0:1], v[72:73] op_sel_hi:[0,1]
	v_pk_mul_f32 v[70:71], v[0:1], v[70:71] op_sel_hi:[0,1]
	v_pk_mul_f32 v[68:69], v[0:1], v[68:69] op_sel_hi:[0,1]
	v_pk_mul_f32 v[66:67], v[0:1], v[66:67] op_sel_hi:[0,1]
	v_pk_mul_f32 v[64:65], v[0:1], v[64:65] op_sel_hi:[0,1]
	v_pk_mul_f32 v[62:63], v[0:1], v[62:63] op_sel_hi:[0,1]
	v_pk_mul_f32 v[60:61], v[0:1], v[60:61] op_sel_hi:[0,1]
	v_pk_mul_f32 v[58:59], v[0:1], v[58:59] op_sel_hi:[0,1]
	v_pk_mul_f32 v[56:57], v[0:1], v[56:57] op_sel_hi:[0,1]
	v_pk_mul_f32 v[54:55], v[0:1], v[54:55] op_sel_hi:[0,1]
	v_pk_mul_f32 v[52:53], v[0:1], v[52:53] op_sel_hi:[0,1]
	v_pk_mul_f32 v[50:51], v[0:1], v[50:51] op_sel_hi:[0,1]
	v_pk_mul_f32 v[48:49], v[0:1], v[48:49] op_sel_hi:[0,1]
	v_pk_mul_f32 v[46:47], v[0:1], v[46:47] op_sel_hi:[0,1]
	v_pk_mul_f32 v[44:45], v[0:1], v[44:45] op_sel_hi:[0,1]
	v_pk_mul_f32 v[42:43], v[0:1], v[42:43] op_sel_hi:[0,1]
	v_pk_mul_f32 v[40:41], v[0:1], v[40:41] op_sel_hi:[0,1]
	v_pk_mul_f32 v[38:39], v[0:1], v[38:39] op_sel_hi:[0,1]
	v_pk_mul_f32 v[36:37], v[0:1], v[36:37] op_sel_hi:[0,1]
	v_pk_mul_f32 v[34:35], v[0:1], v[34:35] op_sel_hi:[0,1]
	v_pk_mul_f32 v[32:33], v[0:1], v[32:33] op_sel_hi:[0,1]
	v_pk_mul_f32 v[30:31], v[0:1], v[30:31] op_sel_hi:[0,1]
	v_pk_mul_f32 v[28:29], v[0:1], v[28:29] op_sel_hi:[0,1]
	v_pk_mul_f32 v[26:27], v[0:1], v[26:27] op_sel_hi:[0,1]
	v_pk_mul_f32 v[24:25], v[0:1], v[24:25] op_sel_hi:[0,1]
	v_pk_mul_f32 v[22:23], v[0:1], v[22:23] op_sel_hi:[0,1]
	v_pk_mul_f32 v[20:21], v[0:1], v[20:21] op_sel_hi:[0,1]
	v_pk_mul_f32 v[18:19], v[0:1], v[18:19] op_sel_hi:[0,1]
	v_pk_mul_f32 v[16:17], v[0:1], v[16:17] op_sel_hi:[0,1]

.LBB0_582:
	s_add_i32 s13, s12, -1
	s_min_u32 s34, s13, s4
	s_lshl_b64 s[30:31], s[34:35], 13
	v_lshl_add_u64 v[2:3], v[216:217], 0, s[30:31]
	global_load_dwordx4 v[196:199], v[2:3], off
	v_add_co_u32_e32 v2, vcc, s1, v212
	s_nop 1
	v_addc_co_u32_e32 v3, vcc, -1, v213, vcc
	global_load_dwordx4 v[200:203], v[2:3], off offset:-4096
	global_load_dwordx4 v[204:207], v[2:3], off
	ds_read_b128 v[2:5], v243 offset:4608
	ds_read_b128 v[6:9], v243
	ds_read_b128 v[12:15], v242 offset:59392
	s_waitcnt lgkmcnt(0)
	v_mfma_f32_32x32x16_bf16 v[160:175], v[6:9], v[12:15], v[96:111]
	ds_read_b128 v[112:115], v243 offset:32
	v_exp_f32_e32 v0, v128
	v_exp_f32_e32 v6, v129
	ds_read_b128 v[116:119], v242 offset:60416
	v_add_f32_e32 v11, v6, v0
	v_cvt_pk_bf16_f32 v10, v0, v6
	v_mfma_f32_32x32x16_bf16 v[144:159], v[2:5], v[12:15], v[96:111]
	ds_read_b128 v[6:9], v243 offset:4640
	v_exp_f32_e32 v0, v130
	v_exp_f32_e32 v120, v131
	v_add_f32_e32 v121, v0, v11
	v_cvt_pk_bf16_f32 v11, v0, v120
	v_add_f32_e32 v0, v120, v121
	s_waitcnt lgkmcnt(1)
	v_mfma_f32_32x32x16_bf16 v[160:175], v[112:115], v[116:119], v[160:175]
	ds_read_b128 v[2:5], v243 offset:64
	ds_read_b128 v[120:123], v242 offset:61440
	v_exp_f32_e32 v12, v132
	v_exp_f32_e32 v13, v133
	v_add_f32_e32 v0, v12, v0
	v_add_f32_e32 v0, v13, v0
	v_cvt_pk_bf16_f32 v12, v12, v13
	s_waitcnt lgkmcnt(2)
	v_mfma_f32_32x32x16_bf16 v[144:159], v[6:9], v[116:119], v[144:159]
	ds_read_b128 v[112:115], v243 offset:4672
	v_exp_f32_e32 v6, v134
	v_exp_f32_e32 v7, v135
	v_add_f32_e32 v0, v6, v0
	v_add_f32_e32 v0, v7, v0
	v_cvt_pk_bf16_f32 v13, v6, v7
	s_waitcnt lgkmcnt(1)
	v_mfma_f32_32x32x16_bf16 v[160:175], v[2:5], v[120:123], v[160:175]
	ds_read_b128 v[116:119], v243 offset:96
	ds_read_b128 v[124:127], v242 offset:62464
	v_exp_f32_e32 v2, v136
	v_exp_f32_e32 v3, v137
	v_add_f32_e32 v0, v2, v0
	v_add_f32_e32 v0, v3, v0
	v_cvt_pk_bf16_f32 v6, v2, v3
	s_waitcnt lgkmcnt(2)
	v_mfma_f32_32x32x16_bf16 v[144:159], v[112:115], v[120:123], v[144:159]
	ds_read_b128 v[2:5], v243 offset:4704
	v_exp_f32_e32 v7, v138
	v_exp_f32_e32 v8, v139
	v_add_f32_e32 v0, v7, v0
	v_add_f32_e32 v0, v8, v0
	v_cvt_pk_bf16_f32 v7, v7, v8
	s_waitcnt lgkmcnt(1)
	v_mfma_f32_32x32x16_bf16 v[160:175], v[116:119], v[124:127], v[160:175]
	ds_read_b64_tr_b16 v[112:113], v244 offset:18432
	ds_read_b64_tr_b16 v[114:115], v244 offset:20992
	v_exp_f32_e32 v8, v140
	v_exp_f32_e32 v9, v141
	v_add_f32_e32 v0, v8, v0
	v_add_f32_e32 v0, v9, v0
	v_cvt_pk_bf16_f32 v8, v8, v9
	s_waitcnt lgkmcnt(2)
	v_mfma_f32_32x32x16_bf16 v[144:159], v[2:5], v[124:127], v[144:159]
	ds_read_b64_tr_b16 v[116:117], v244 offset:18496
	ds_read_b64_tr_b16 v[118:119], v244 offset:21056
	v_exp_f32_e32 v9, v142
	v_exp_f32_e32 v14, v143
	v_add_f32_e32 v0, v9, v0
	v_add_f32_e32 v0, v14, v0
	v_cvt_pk_bf16_f32 v9, v9, v14
	s_waitcnt lgkmcnt(2)
	v_mfma_f32_32x32x16_bf16 v[64:79], v[112:115], v[188:191], v[64:79]
	ds_read_b64_tr_b16 v[120:121], v244 offset:18560
	ds_read_b64_tr_b16 v[122:123], v244 offset:21120
	v_exp_f32_e32 v2, v80
	v_max3_f32 v3, v160, s33, v144
	v_add_f32_e32 v0, v2, v0
	s_waitcnt lgkmcnt(2)
	v_mfma_f32_32x32x16_bf16 v[48:63], v[116:119], v[188:191], v[48:63]
	ds_read_b64_tr_b16 v[112:113], v244 offset:18624
	ds_read_b64_tr_b16 v[114:115], v244 offset:21184
	v_exp_f32_e32 v4, v81
	v_max3_f32 v3, v3, v161, v145
	v_add_f32_e32 v0, v4, v0
	v_cvt_pk_bf16_f32 v2, v2, v4
	s_waitcnt lgkmcnt(2)
	v_mfma_f32_32x32x16_bf16 v[32:47], v[120:123], v[188:191], v[32:47]
	ds_read_b64_tr_b16 v[116:117], v244 offset:23552
	ds_read_b64_tr_b16 v[118:119], v244 offset:26112
	v_exp_f32_e32 v4, v82
	v_max3_f32 v5, v3, v162, v146
	v_add_f32_e32 v0, v4, v0
	s_waitcnt lgkmcnt(2)
	v_mfma_f32_32x32x16_bf16 v[16:31], v[112:115], v[188:191], v[16:31]
	ds_read_b64_tr_b16 v[120:121], v244 offset:23616
	v_exp_f32_e32 v3, v83
	ds_read_b64_tr_b16 v[122:123], v244 offset:26176
	v_add_f32_e32 v0, v3, v0
	v_cvt_pk_bf16_f32 v3, v4, v3
	v_max3_f32 v4, v5, v163, v147
	s_waitcnt lgkmcnt(2)
	v_mfma_f32_32x32x16_bf16 v[64:79], v[116:119], v[184:187], v[64:79]
	ds_read_b64_tr_b16 v[80:81], v244 offset:23680
	ds_read_b64_tr_b16 v[82:83], v244 offset:26240
	v_exp_f32_e32 v5, v84
	v_max3_f32 v14, v4, v164, v148
	v_add_f32_e32 v0, v5, v0
	s_waitcnt lgkmcnt(2)
	v_mfma_f32_32x32x16_bf16 v[48:63], v[120:123], v[184:187], v[48:63]
	ds_read_b64_tr_b16 v[112:113], v244 offset:23744
	v_exp_f32_e32 v4, v85
	ds_read_b64_tr_b16 v[114:115], v244 offset:26304
	v_add_f32_e32 v0, v4, v0
	v_cvt_pk_bf16_f32 v4, v5, v4
	v_max3_f32 v5, v14, v165, v149
	s_waitcnt lgkmcnt(2)
	v_mfma_f32_32x32x16_bf16 v[32:47], v[80:83], v[184:187], v[32:47]
	ds_read_b64_tr_b16 v[116:117], v244 offset:28672
	ds_read_b64_tr_b16 v[118:119], v244 offset:31232
	v_exp_f32_e32 v14, v86
	v_max3_f32 v15, v5, v166, v150
	v_add_f32_e32 v0, v14, v0
	s_waitcnt lgkmcnt(2)
	v_mfma_f32_32x32x16_bf16 v[16:31], v[112:115], v[184:187], v[16:31]
	ds_read_b64_tr_b16 v[80:81], v244 offset:28736
	v_exp_f32_e32 v5, v87
	ds_read_b64_tr_b16 v[82:83], v244 offset:31296
	v_add_f32_e32 v0, v5, v0
	v_cvt_pk_bf16_f32 v5, v14, v5
	v_max3_f32 v14, v15, v167, v151
	s_waitcnt lgkmcnt(2)
	v_mfma_f32_32x32x16_bf16 v[64:79], v[116:119], v[176:179], v[64:79]
	ds_read_b64_tr_b16 v[84:85], v244 offset:28800
	ds_read_b64_tr_b16 v[86:87], v244 offset:31360
	v_exp_f32_e32 v15, v88
	v_max3_f32 v14, v14, v168, v152
	v_add_f32_e32 v0, v15, v0
	s_waitcnt lgkmcnt(2)
	v_mfma_f32_32x32x16_bf16 v[48:63], v[80:83], v[176:179], v[48:63]
	ds_read_b64_tr_b16 v[112:113], v244 offset:28864
	ds_read_b64_tr_b16 v[114:115], v244 offset:31424
	v_exp_f32_e32 v80, v89
	v_max3_f32 v14, v14, v169, v153
	v_add_f32_e32 v0, v80, v0
	v_cvt_pk_bf16_f32 v192, v15, v80
	s_waitcnt lgkmcnt(2)
	v_mfma_f32_32x32x16_bf16 v[32:47], v[84:87], v[176:179], v[32:47]
	ds_read_b64_tr_b16 v[80:81], v244 offset:33792
	ds_read_b64_tr_b16 v[82:83], v244 offset:36352
	v_exp_f32_e32 v15, v90
	v_max3_f32 v14, v14, v170, v154
	v_add_f32_e32 v0, v15, v0
	s_waitcnt lgkmcnt(2)
	v_mfma_f32_32x32x16_bf16 v[16:31], v[112:115], v[176:179], v[16:31]
	ds_read_b64_tr_b16 v[84:85], v244 offset:33856
	ds_read_b64_tr_b16 v[86:87], v244 offset:36416
	v_exp_f32_e32 v88, v91
	v_max3_f32 v14, v14, v171, v155
	v_add_f32_e32 v0, v88, v0
	v_cvt_pk_bf16_f32 v193, v15, v88
	s_waitcnt lgkmcnt(2)
	v_mfma_f32_32x32x16_bf16 v[64:79], v[80:83], v[180:183], v[64:79]
	ds_read_b64_tr_b16 v[88:89], v244 offset:33920
	ds_read_b64_tr_b16 v[90:91], v244 offset:36480
	v_exp_f32_e32 v15, v92
	v_max3_f32 v14, v14, v172, v156
	v_add_f32_e32 v0, v15, v0
	s_waitcnt lgkmcnt(2)
	v_mfma_f32_32x32x16_bf16 v[48:63], v[84:87], v[180:183], v[48:63]
	ds_read_b64_tr_b16 v[80:81], v244 offset:33984
	ds_read_b64_tr_b16 v[82:83], v244 offset:36544
	v_exp_f32_e32 v84, v93
	v_max3_f32 v14, v14, v173, v157
	v_add_f32_e32 v0, v84, v0
	v_cvt_pk_bf16_f32 v194, v15, v84
	s_waitcnt lgkmcnt(2)
	v_mfma_f32_32x32x16_bf16 v[32:47], v[88:91], v[180:183], v[32:47]
	v_exp_f32_e32 v15, v94
	v_max3_f32 v14, v14, v174, v158
	v_add_f32_e32 v0, v15, v0
	s_waitcnt lgkmcnt(0)
	v_mfma_f32_32x32x16_bf16 v[16:31], v[80:83], v[180:183], v[16:31]
	v_exp_f32_e32 v80, v95
	s_nop 0
	v_add_f32_e32 v0, v80, v0
	v_cvt_pk_bf16_f32 v195, v15, v80
	v_max3_f32 v15, v14, v175, v159
	v_mov_b32_e32 v14, v0
	v_cmp_gt_f32_e32 vcc, 1.0, v220
	s_nop 0
	v_permlane32_swap_b32_e32 v0, v14
	s_cbranch_vccz .LBB0_584
	v_pk_mul_f32 v[78:79], v[220:221], v[78:79] op_sel_hi:[0,1]
	v_pk_mul_f32 v[76:77], v[220:221], v[76:77] op_sel_hi:[0,1]
	v_pk_mul_f32 v[74:75], v[220:221], v[74:75] op_sel_hi:[0,1]
	v_pk_mul_f32 v[72:73], v[220:221], v[72:73] op_sel_hi:[0,1]
	v_pk_mul_f32 v[70:71], v[220:221], v[70:71] op_sel_hi:[0,1]
	v_pk_mul_f32 v[68:69], v[220:221], v[68:69] op_sel_hi:[0,1]
	v_pk_mul_f32 v[66:67], v[220:221], v[66:67] op_sel_hi:[0,1]
	v_pk_mul_f32 v[64:65], v[220:221], v[64:65] op_sel_hi:[0,1]
	v_pk_mul_f32 v[62:63], v[220:221], v[62:63] op_sel_hi:[0,1]
	v_pk_mul_f32 v[60:61], v[220:221], v[60:61] op_sel_hi:[0,1]
	v_pk_mul_f32 v[58:59], v[220:221], v[58:59] op_sel_hi:[0,1]
	v_pk_mul_f32 v[56:57], v[220:221], v[56:57] op_sel_hi:[0,1]
	v_pk_mul_f32 v[54:55], v[220:221], v[54:55] op_sel_hi:[0,1]
	v_pk_mul_f32 v[52:53], v[220:221], v[52:53] op_sel_hi:[0,1]
	v_pk_mul_f32 v[50:51], v[220:221], v[50:51] op_sel_hi:[0,1]
	v_pk_mul_f32 v[48:49], v[220:221], v[48:49] op_sel_hi:[0,1]
	v_pk_mul_f32 v[46:47], v[220:221], v[46:47] op_sel_hi:[0,1]
	v_pk_mul_f32 v[44:45], v[220:221], v[44:45] op_sel_hi:[0,1]
	v_pk_mul_f32 v[42:43], v[220:221], v[42:43] op_sel_hi:[0,1]
	v_pk_mul_f32 v[40:41], v[220:221], v[40:41] op_sel_hi:[0,1]
	v_pk_mul_f32 v[38:39], v[220:221], v[38:39] op_sel_hi:[0,1]
	v_pk_mul_f32 v[36:37], v[220:221], v[36:37] op_sel_hi:[0,1]
	v_pk_mul_f32 v[34:35], v[220:221], v[34:35] op_sel_hi:[0,1]
	v_pk_mul_f32 v[32:33], v[220:221], v[32:33] op_sel_hi:[0,1]
	v_pk_mul_f32 v[30:31], v[220:221], v[30:31] op_sel_hi:[0,1]
	v_pk_mul_f32 v[28:29], v[220:221], v[28:29] op_sel_hi:[0,1]
	v_pk_mul_f32 v[26:27], v[220:221], v[26:27] op_sel_hi:[0,1]
	v_pk_mul_f32 v[24:25], v[220:221], v[24:25] op_sel_hi:[0,1]
	v_pk_mul_f32 v[22:23], v[220:221], v[22:23] op_sel_hi:[0,1]
	v_pk_mul_f32 v[20:21], v[220:221], v[20:21] op_sel_hi:[0,1]
	v_pk_mul_f32 v[18:19], v[220:221], v[18:19] op_sel_hi:[0,1]
	v_pk_mul_f32 v[16:17], v[220:221], v[16:17] op_sel_hi:[0,1]

.LBB0_587:
	s_min_u32 s34, s12, s4
	s_waitcnt vmcnt(2)
	ds_write_b128 v241, v[196:199] offset:9216
	s_waitcnt vmcnt(1)
	ds_write_b128 v240, v[200:203] offset:38912
	s_waitcnt vmcnt(0)
	ds_write_b128 v240, v[204:207] offset:49152
	s_lshl_b64 s[30:31], s[34:35], 13
	s_waitcnt lgkmcnt(0)
	s_barrier
	v_lshl_add_u64 v[80:81], v[216:217], 0, s[30:31]
	global_load_dwordx4 v[196:199], v[80:81], off
	global_load_dwordx4 v[200:203], v[212:213], off offset:-4096
	global_load_dwordx4 v[204:207], v[212:213], off
	ds_read_b128 v[176:179], v243 offset:13824
	ds_read_b128 v[80:83], v243 offset:9216
	ds_read_b128 v[180:183], v242 offset:59392
	s_waitcnt lgkmcnt(0)
	v_mfma_f32_32x32x16_bf16 v[128:143], v[80:83], v[180:183], v[112:127]
	ds_read_b128 v[184:187], v243 offset:9248
	v_exp_f32_e32 v15, v160
	v_exp_f32_e32 v80, v161
	ds_read_b128 v[222:225], v242 offset:60416
	v_add_f32_e32 v81, v80, v15
	v_cvt_pk_bf16_f32 v188, v15, v80
	v_exp_f32_e32 v15, v162
	v_exp_f32_e32 v80, v163
	ds_read_b128 v[160:163], v243 offset:13856
	v_add_f32_e32 v81, v15, v81
	v_cvt_pk_bf16_f32 v189, v15, v80
	v_add_f32_e32 v15, v80, v81
	v_mfma_f32_32x32x16_bf16 v[80:95], v[176:179], v[180:183], v[112:127]
	s_waitcnt lgkmcnt(1)
	v_mfma_f32_32x32x16_bf16 v[128:143], v[184:187], v[222:225], v[128:143]
	ds_read_b128 v[176:179], v243 offset:9280
	ds_read_b128 v[180:183], v242 offset:61440
	v_exp_f32_e32 v164, v164
	v_exp_f32_e32 v165, v165
	v_add_f32_e32 v15, v164, v15
	v_cvt_pk_bf16_f32 v190, v164, v165
	v_add_f32_e32 v15, v165, v15
	s_waitcnt lgkmcnt(2)
	v_mfma_f32_32x32x16_bf16 v[80:95], v[160:163], v[222:225], v[80:95]
	ds_read_b128 v[234:237], v243 offset:13888
	v_exp_f32_e32 v160, v166
	v_exp_f32_e32 v161, v167
	v_add_f32_e32 v15, v160, v15
	v_cvt_pk_bf16_f32 v191, v160, v161
	v_add_f32_e32 v15, v161, v15
	s_waitcnt lgkmcnt(1)
	v_mfma_f32_32x32x16_bf16 v[128:143], v[176:179], v[180:183], v[128:143]
	ds_read_b128 v[160:163], v243 offset:9312
	ds_read_b128 v[164:167], v242 offset:62464
	v_exp_f32_e32 v168, v168
	v_exp_f32_e32 v169, v169
	v_add_f32_e32 v15, v168, v15
	v_cvt_pk_bf16_f32 v184, v168, v169
	v_add_f32_e32 v15, v169, v15
	s_waitcnt lgkmcnt(2)
	v_mfma_f32_32x32x16_bf16 v[80:95], v[234:237], v[180:183], v[80:95]
	ds_read_b128 v[176:179], v243 offset:13920
	v_exp_f32_e32 v168, v170
	v_exp_f32_e32 v169, v171
	v_add_f32_e32 v15, v168, v15
	v_cvt_pk_bf16_f32 v185, v168, v169
	v_add_f32_e32 v15, v169, v15
	s_waitcnt lgkmcnt(1)
	v_mfma_f32_32x32x16_bf16 v[128:143], v[160:163], v[164:167], v[128:143]
	ds_read_b64_tr_b16 v[168:169], v244 offset:38912
	ds_read_b64_tr_b16 v[170:171], v244 offset:41472
	v_exp_f32_e32 v160, v172
	v_exp_f32_e32 v161, v173
	v_add_f32_e32 v15, v160, v15
	v_cvt_pk_bf16_f32 v186, v160, v161
	v_add_f32_e32 v15, v161, v15
	s_waitcnt lgkmcnt(2)
	v_mfma_f32_32x32x16_bf16 v[80:95], v[176:179], v[164:167], v[80:95]
	ds_read_b64_tr_b16 v[160:161], v244 offset:38976
	ds_read_b64_tr_b16 v[162:163], v244 offset:41536
	v_exp_f32_e32 v172, v174
	v_exp_f32_e32 v173, v175
	v_add_f32_e32 v15, v172, v15
	v_cvt_pk_bf16_f32 v187, v172, v173
	v_add_f32_e32 v15, v173, v15
	s_waitcnt lgkmcnt(2)
	v_mfma_f32_32x32x16_bf16 v[64:79], v[168:171], v[10:13], v[64:79]
	ds_read_b64_tr_b16 v[164:165], v244 offset:39040
	ds_read_b64_tr_b16 v[166:167], v244 offset:41600
	v_exp_f32_e32 v144, v144
	v_max3_f32 v172, v128, s33, v80
	v_add_f32_e32 v15, v144, v15
	s_waitcnt lgkmcnt(2)
	v_mfma_f32_32x32x16_bf16 v[48:63], v[160:163], v[10:13], v[48:63]
	ds_read_b64_tr_b16 v[168:169], v244 offset:39104
	v_exp_f32_e32 v145, v145
	ds_read_b64_tr_b16 v[170:171], v244 offset:41664
	v_cvt_pk_bf16_f32 v176, v144, v145
	v_max3_f32 v144, v172, v129, v81
	v_add_f32_e32 v15, v145, v15
	s_waitcnt lgkmcnt(2)
	v_mfma_f32_32x32x16_bf16 v[32:47], v[164:167], v[10:13], v[32:47]
	ds_read_b64_tr_b16 v[160:161], v244 offset:44032
	ds_read_b64_tr_b16 v[162:163], v244 offset:46592
	v_exp_f32_e32 v145, v146
	v_max3_f32 v144, v144, v130, v82
	v_add_f32_e32 v15, v145, v15
	s_waitcnt lgkmcnt(2)
	v_mfma_f32_32x32x16_bf16 v[16:31], v[168:171], v[10:13], v[16:31]
	ds_read_b64_tr_b16 v[164:165], v244 offset:44096
	ds_read_b64_tr_b16 v[166:167], v244 offset:46656
	v_exp_f32_e32 v10, v147
	v_max3_f32 v144, v144, v131, v83
	v_cvt_pk_bf16_f32 v177, v145, v10
	v_add_f32_e32 v15, v10, v15
	s_waitcnt lgkmcnt(2)
	v_mfma_f32_32x32x16_bf16 v[64:79], v[160:163], v[6:9], v[64:79]
	ds_read_b64_tr_b16 v[10:11], v244 offset:44160
	ds_read_b64_tr_b16 v[12:13], v244 offset:46720
	v_exp_f32_e32 v148, v148
	v_max3_f32 v160, v144, v132, v84
	v_add_f32_e32 v15, v148, v15
	s_waitcnt lgkmcnt(2)
	v_mfma_f32_32x32x16_bf16 v[48:63], v[164:167], v[6:9], v[48:63]
	ds_read_b64_tr_b16 v[144:145], v244 offset:44224
	v_exp_f32_e32 v149, v149
	ds_read_b64_tr_b16 v[146:147], v244 offset:46784
	v_cvt_pk_bf16_f32 v178, v148, v149
	v_max3_f32 v148, v160, v133, v85
	v_add_f32_e32 v15, v149, v15
	s_waitcnt lgkmcnt(2)
	v_mfma_f32_32x32x16_bf16 v[32:47], v[10:13], v[6:9], v[32:47]
	ds_read_b64_tr_b16 v[160:161], v244 offset:49152
	ds_read_b64_tr_b16 v[162:163], v244 offset:51712
	v_exp_f32_e32 v149, v150
	v_max3_f32 v148, v148, v134, v86
	v_add_f32_e32 v15, v149, v15
	s_waitcnt lgkmcnt(2)
	v_mfma_f32_32x32x16_bf16 v[16:31], v[144:147], v[6:9], v[16:31]
	ds_read_b64_tr_b16 v[10:11], v244 offset:49216
	ds_read_b64_tr_b16 v[12:13], v244 offset:51776
	v_exp_f32_e32 v6, v151
	v_max3_f32 v144, v148, v135, v87
	v_cvt_pk_bf16_f32 v179, v149, v6
	v_add_f32_e32 v15, v6, v15
	s_waitcnt lgkmcnt(2)
	v_mfma_f32_32x32x16_bf16 v[64:79], v[160:163], v[2:5], v[64:79]
	ds_read_b64_tr_b16 v[6:7], v244 offset:49280
	ds_read_b64_tr_b16 v[8:9], v244 offset:51840
	v_exp_f32_e32 v148, v152
	v_max3_f32 v149, v144, v136, v88
	v_add_f32_e32 v15, v148, v15
	s_waitcnt lgkmcnt(2)
	v_mfma_f32_32x32x16_bf16 v[48:63], v[10:13], v[2:5], v[48:63]
	ds_read_b64_tr_b16 v[144:145], v244 offset:49344
	v_exp_f32_e32 v10, v153
	ds_read_b64_tr_b16 v[146:147], v244 offset:51904
	v_cvt_pk_bf16_f32 v180, v148, v10
	v_max3_f32 v148, v149, v137, v89
	v_add_f32_e32 v15, v10, v15
	s_waitcnt lgkmcnt(2)
	v_mfma_f32_32x32x16_bf16 v[32:47], v[6:9], v[2:5], v[32:47]
	ds_read_b64_tr_b16 v[10:11], v244 offset:54272
	ds_read_b64_tr_b16 v[12:13], v244 offset:56832
	v_exp_f32_e32 v149, v154
	v_max3_f32 v148, v148, v138, v90
	v_add_f32_e32 v15, v149, v15
	s_waitcnt lgkmcnt(2)
	v_mfma_f32_32x32x16_bf16 v[16:31], v[144:147], v[2:5], v[16:31]
	ds_read_b64_tr_b16 v[6:7], v244 offset:54336
	ds_read_b64_tr_b16 v[8:9], v244 offset:56896
	v_exp_f32_e32 v2, v155
	v_max3_f32 v144, v148, v139, v91
	v_cvt_pk_bf16_f32 v181, v149, v2
	v_add_f32_e32 v15, v2, v15
	s_waitcnt lgkmcnt(2)
	v_mfma_f32_32x32x16_bf16 v[64:79], v[10:13], v[192:195], v[64:79]
	ds_read_b64_tr_b16 v[2:3], v244 offset:54400
	ds_read_b64_tr_b16 v[4:5], v244 offset:56960
	v_exp_f32_e32 v145, v156
	v_max3_f32 v144, v144, v140, v92
	v_add_f32_e32 v15, v145, v15
	s_waitcnt lgkmcnt(2)
	v_mfma_f32_32x32x16_bf16 v[48:63], v[6:9], v[192:195], v[48:63]
	ds_read_b64_tr_b16 v[10:11], v244 offset:54464
	v_exp_f32_e32 v6, v157
	ds_read_b64_tr_b16 v[12:13], v244 offset:57024
	v_add_f32_e32 v7, v6, v15
	v_cvt_pk_bf16_f32 v182, v145, v6
	v_max3_f32 v6, v144, v141, v93
	s_waitcnt lgkmcnt(2)
	v_mfma_f32_32x32x16_bf16 v[32:47], v[2:5], v[192:195], v[32:47]
	v_exp_f32_e32 v3, v158
	v_max3_f32 v4, v6, v142, v94
	v_add_f32_e32 v2, v3, v7
	s_waitcnt lgkmcnt(0)
	v_mfma_f32_32x32x16_bf16 v[16:31], v[10:13], v[192:195], v[16:31]
	v_exp_f32_e32 v5, v159
	s_nop 0
	v_add_f32_e32 v2, v5, v2
	v_cvt_pk_bf16_f32 v183, v3, v5
	v_max3_f32 v3, v4, v143, v95
	v_mov_b32_e32 v4, v2
	v_cmp_gt_f32_e32 vcc, 1.0, v0
	s_nop 0
	v_permlane32_swap_b32_e32 v2, v4
	s_cbranch_vccz .LBB0_589
	v_pk_mul_f32 v[78:79], v[0:1], v[78:79] op_sel_hi:[0,1]
	v_pk_mul_f32 v[76:77], v[0:1], v[76:77] op_sel_hi:[0,1]
	v_pk_mul_f32 v[74:75], v[0:1], v[74:75] op_sel_hi:[0,1]
	v_pk_mul_f32 v[72:73], v[0:1], v[72:73] op_sel_hi:[0,1]
	v_pk_mul_f32 v[70:71], v[0:1], v[70:71] op_sel_hi:[0,1]
	v_pk_mul_f32 v[68:69], v[0:1], v[68:69] op_sel_hi:[0,1]
	v_pk_mul_f32 v[66:67], v[0:1], v[66:67] op_sel_hi:[0,1]
	v_pk_mul_f32 v[64:65], v[0:1], v[64:65] op_sel_hi:[0,1]
	v_pk_mul_f32 v[62:63], v[0:1], v[62:63] op_sel_hi:[0,1]
	v_pk_mul_f32 v[60:61], v[0:1], v[60:61] op_sel_hi:[0,1]
	v_pk_mul_f32 v[58:59], v[0:1], v[58:59] op_sel_hi:[0,1]
	v_pk_mul_f32 v[56:57], v[0:1], v[56:57] op_sel_hi:[0,1]
	v_pk_mul_f32 v[54:55], v[0:1], v[54:55] op_sel_hi:[0,1]
	v_pk_mul_f32 v[52:53], v[0:1], v[52:53] op_sel_hi:[0,1]
	v_pk_mul_f32 v[50:51], v[0:1], v[50:51] op_sel_hi:[0,1]
	v_pk_mul_f32 v[48:49], v[0:1], v[48:49] op_sel_hi:[0,1]
	v_pk_mul_f32 v[46:47], v[0:1], v[46:47] op_sel_hi:[0,1]
	v_pk_mul_f32 v[44:45], v[0:1], v[44:45] op_sel_hi:[0,1]
	v_pk_mul_f32 v[42:43], v[0:1], v[42:43] op_sel_hi:[0,1]
	v_pk_mul_f32 v[40:41], v[0:1], v[40:41] op_sel_hi:[0,1]
	v_pk_mul_f32 v[38:39], v[0:1], v[38:39] op_sel_hi:[0,1]
	v_pk_mul_f32 v[36:37], v[0:1], v[36:37] op_sel_hi:[0,1]
	v_pk_mul_f32 v[34:35], v[0:1], v[34:35] op_sel_hi:[0,1]
	v_pk_mul_f32 v[32:33], v[0:1], v[32:33] op_sel_hi:[0,1]
	v_pk_mul_f32 v[30:31], v[0:1], v[30:31] op_sel_hi:[0,1]
	v_pk_mul_f32 v[28:29], v[0:1], v[28:29] op_sel_hi:[0,1]
	v_pk_mul_f32 v[26:27], v[0:1], v[26:27] op_sel_hi:[0,1]
	v_pk_mul_f32 v[24:25], v[0:1], v[24:25] op_sel_hi:[0,1]
	v_pk_mul_f32 v[22:23], v[0:1], v[22:23] op_sel_hi:[0,1]
	v_pk_mul_f32 v[20:21], v[0:1], v[20:21] op_sel_hi:[0,1]
	v_pk_mul_f32 v[18:19], v[0:1], v[18:19] op_sel_hi:[0,1]
	v_pk_mul_f32 v[16:17], v[0:1], v[16:17] op_sel_hi:[0,1]
